# v61 with the stagger applied per block (bid bit 8) instead of per wave half
# speedup vs baseline: 1.0047x; 1.0047x over previous
; template <int MODE, bool SWAP, int MT>
; DI void gemm_tile(const int wv_, const Params& p, const u16* __restrict__ A, const u16* __restrict__ Bt, int brow, int bcol, char* smem, const float* gnext) {
;     ...
;   const int tid = tid_, wid = tid >> 6, lane = tid & 63, wr = wid >> 1, wc = wid & 1, fr = lane & 15, fq = lane >> 4;
;   f32x4 acc[MT][4];
; #pragma unroll
;   for (int m = 0; m < MT; ++m)
; #pragma unroll
;     for (int n = 0; n < 4; ++n) acc[m][n] = f32x4{0.f, 0.f, 0.f, 0.f};
;   const int ra = tid >> 2, cb = (tid & 3) * 8;
;   const u16* ga0 = A + (size_t)(brow + ra) * 1024 + cb;
;   const u16* ga1 = A + (size_t)(brow + 128 + ra) * 1024 + cb;
;   const u16* gb0 = Bt + (size_t)(bcol + ra) * 1024 + cb;
;   auto stage = [&](int t, int buf) {
;     char* sA = smem + buf * 24576; char* sB = sA + 16384;
;     if (MT >= 2 || tid < 256) __builtin_amdgcn_global_load_lds((const unsigned*)(ga0 + t * 32), (unsigned*)(sA + tid * 16), 16, 0, 0);
;     if (MT == 4) __builtin_amdgcn_global_load_lds((const unsigned*)(ga1 + t * 32), (unsigned*)(sA + 8192 + tid * 16), 16, 0, 0);
;     __builtin_amdgcn_global_load_lds((const unsigned*)(gb0 + t * 32), (unsigned*)(sB + tid * 16), 16, 0, 0);
;   };
;   stage(0, 0);
;   for (int t = 0; t < 32; ++t) {
;     asm volatile("s_waitcnt vmcnt(0)" ::: "memory");
;     __syncthreads();
;     if (t + 1 < 32) stage(t + 1, (t + 1) & 1);
;     const char* sA = smem + (t & 1) * 24576; const char* sB = sA + 16384;
;     bf16x8 Af[MT], Bf[4];
; #pragma unroll
;     for (int n = 0; n < 4; ++n) Bf[n] = *(const bf16x8*)(sB + (wc * 64 + n * 16 + fr) * 64 + fq * 16);
;     constexpr int MH = MT >= 2 ? MT / 2 : 1;
; #pragma unroll
;     for (int m = 0; m < MH; ++m) Af[m] = *(const bf16x8*)(sA + (wr * (16 * MT) + m * 16 + fr) * 64 + fq * 16);
.LBB0_84:
	s_mul_hi_i32 s0, s14, 0x92492493
	s_add_i32 s0, s0, s14
	s_lshr_b32 s1, s0, 31
	s_ashr_i32 s0, s0, 4
	s_add_i32 s19, s0, s1
	s_mul_i32 s0, s19, 0xffffffe4
	s_add_i32 s0, s0, s14
	s_and_b32 s1, s0, -4
	s_lshl_b32 s18, s19, 8
	s_lshl_b32 s15, s0, 7
	s_cmp_lg_u32 s1, 20
	s_mov_b64 s[0:1], -1
	s_mulk_i32 s19, 0xe00
	s_cbranch_scc0 .LBB0_88
	s_mov_b32 s1, 0
	v_readlane_b32 s20, v127, 0
	v_mbcnt_lo_u32_b32 v0, -1, s1
	v_mbcnt_hi_u32_b32 v0, -1, v0
	v_add_u32_e32 v12, s33, v0
	s_mov_b32 s1, s16
	v_ashrrev_i32_e32 v13, 2, v12
	v_add_u32_e32 v0, s18, v13
	s_mov_b32 s1, s17
	v_ashrrev_i32_e32 v1, 31, v0
	v_lshlrev_b64 v[4:5], 11, v[0:1]
	v_readlane_b32 s21, v127, 1
	v_lshlrev_b32_e32 v76, 4, v12
	v_lshrrev_b32_e32 v2, 8, v76
	v_sub_u32_e32 v2, 0, v2
	v_lshlrev_b32_e32 v2, 4, v2
	v_xor_b32_e32 v2, v2, v76
	v_and_b32_e32 v2, 48, v2
	v_lshl_add_u64 v[6:7], s[20:21], 0, v[4:5]
	v_add_u32_e32 v0, 0x80, v0
	v_readfirstlane_b32 s1, v76
	v_lshl_add_u64 v[6:7], v[6:7], 0, v[2:3]
	v_ashrrev_i32_e32 v1, 31, v0
	s_mov_b32 m0, s1
	v_lshlrev_b64 v[8:9], 11, v[0:1]
	global_load_lds_dwordx4 v[6:7], off
	v_add_u32_e32 v6, 0x2000, v76
	v_lshl_add_u64 v[0:1], s[20:21], 0, v[8:9]
	v_add_u32_e32 v10, s15, v13
	v_readfirstlane_b32 s1, v6
	v_lshl_add_u64 v[0:1], v[0:1], 0, v[2:3]
	v_ashrrev_i32_e32 v11, 31, v10
	s_mov_b32 m0, s1
	v_lshlrev_b64 v[10:11], 11, v[10:11]
	global_load_lds_dwordx4 v[0:1], off
	v_add_u32_e32 v0, 0x4000, v76
	v_lshl_add_u64 v[10:11], s[2:3], 0, v[10:11]
	v_readfirstlane_b32 s1, v0
	v_lshl_add_u64 v[10:11], v[10:11], 0, v[2:3]
	s_mov_b32 m0, s1
	v_and_b32_e32 v74, 15, v12
	global_load_lds_dwordx4 v[10:11], off
	v_readlane_b32 s20, v127, 22
	v_bfe_u32 v72, v12, 6, 1
	v_ashrrev_i32_e32 v73, 7, v12
	v_lshlrev_b32_e32 v0, 6, v74
	v_or_b32_e32 v4, v4, v2
	v_readlane_b32 s21, v127, 23
	v_lshl_or_b32 v78, v72, 12, v0
	v_lshl_or_b32 v79, v73, 12, v0
	v_lshl_add_u64 v[0:1], s[20:21], 0, v[4:5]
	v_add_u32_e32 v4, s12, v13
	v_subrev_u32_e32 v4, s19, v4
	v_ashrrev_i32_e32 v5, 31, v4
	v_lshlrev_b64 v[4:5], 11, v[4:5]
	v_or_b32_e32 v4, v4, v2
	v_bfe_u32 v75, v12, 4, 2
	v_or_b32_e32 v8, v8, v2
	v_lshl_add_u64 v[70:71], s[4:5], 0, v[4:5]
	v_mov_b32_e32 v4, 0
	s_mov_b32 s0, 0
	v_lshrrev_b32_e32 v77, 2, v74
	v_sub_u32_e32 v77, 0, v77
	v_xor_b32_e32 v77, v77, v75
	v_and_b32_e32 v77, 3, v77
	v_lshlrev_b32_e32 v77, 4, v77
	v_lshl_add_u64 v[68:69], s[20:21], 0, v[8:9]
	v_mov_b32_e32 v5, v4
	v_mov_b32_e32 v6, v4
	v_mov_b32_e32 v7, v4
	v_mov_b32_e32 v8, v4
	v_mov_b32_e32 v9, v4
	v_mov_b32_e32 v10, v4
	v_mov_b32_e32 v11, v4
	v_mov_b32_e32 v12, v4
	v_mov_b32_e32 v13, v4
	v_mov_b32_e32 v14, v4
	v_mov_b32_e32 v15, v4
	v_mov_b32_e32 v16, v4
	v_mov_b32_e32 v17, v4
	v_mov_b32_e32 v18, v4
	v_mov_b32_e32 v19, v4
	v_mov_b32_e32 v20, v4
	v_mov_b32_e32 v21, v4
	v_mov_b32_e32 v22, v4
	v_mov_b32_e32 v23, v4
	v_mov_b32_e32 v24, v4
	v_mov_b32_e32 v25, v4
	v_mov_b32_e32 v26, v4
	v_mov_b32_e32 v27, v4
	v_mov_b32_e32 v28, v4
	v_mov_b32_e32 v29, v4
	v_mov_b32_e32 v30, v4
	v_mov_b32_e32 v31, v4
	v_mov_b32_e32 v32, v4
	v_mov_b32_e32 v33, v4
	v_mov_b32_e32 v34, v4
	v_mov_b32_e32 v35, v4
	v_mov_b32_e32 v44, v4
	v_mov_b32_e32 v45, v4
	v_mov_b32_e32 v46, v4
	v_mov_b32_e32 v47, v4
	v_mov_b32_e32 v36, v4
	v_mov_b32_e32 v37, v4
	v_mov_b32_e32 v38, v4
	v_mov_b32_e32 v39, v4
	v_mov_b32_e32 v40, v4
	v_mov_b32_e32 v41, v4
	v_mov_b32_e32 v42, v4
	v_mov_b32_e32 v43, v4
	v_mov_b32_e32 v48, v4
	v_mov_b32_e32 v49, v4
	v_mov_b32_e32 v50, v4
	v_mov_b32_e32 v51, v4
	v_mov_b32_e32 v52, v4
	v_mov_b32_e32 v53, v4
	v_mov_b32_e32 v54, v4
	v_mov_b32_e32 v55, v4
	v_mov_b32_e32 v56, v4
	v_mov_b32_e32 v57, v4
	v_mov_b32_e32 v58, v4
	v_mov_b32_e32 v59, v4
	v_mov_b32_e32 v60, v4
	v_mov_b32_e32 v61, v4
	v_mov_b32_e32 v62, v4
	v_mov_b32_e32 v63, v4
	v_mov_b32_e32 v64, v4
	v_mov_b32_e32 v65, v4
	v_mov_b32_e32 v66, v4
	v_mov_b32_e32 v67, v4
	v_readlane_b32 s22, v127, 2
	v_readlane_b32 s23, v127, 3
	v_readfirstlane_b32 s98, v76
	s_movk_i32 s99, 0x6000
	s_add_i32 s101, s98, s99
	s_mov_b32 m0, s101
	s_add_i32 s101, s101, 0x2000
	global_load_lds_dwordx4 v[0:1], off
	s_mov_b32 m0, s101
	s_add_i32 s101, s101, 0x2000
	global_load_lds_dwordx4 v[68:69], off
	s_mov_b32 m0, s101
	s_add_i32 s99, s99, 0x6000
	global_load_lds_dwordx4 v[70:71], off
	s_cmp_eq_u32 s99, 0x12000
	s_cselect_b32 s99, 0, s99
	v_lshl_add_u64 v[0:1], v[0:1], 0, 64
	v_lshl_add_u64 v[68:69], v[68:69], 0, 64
	v_lshl_add_u64 v[70:71], v[70:71], 0, 64
	s_add_i32 s101, s98, s99
	s_mov_b32 m0, s101
	s_add_i32 s101, s101, 0x2000
	global_load_lds_dwordx4 v[0:1], off
	s_mov_b32 m0, s101
	s_add_i32 s101, s101, 0x2000
	global_load_lds_dwordx4 v[68:69], off
	s_mov_b32 m0, s101
	s_add_i32 s99, s99, 0x6000
	global_load_lds_dwordx4 v[70:71], off
	s_cmp_eq_u32 s99, 0x12000
	s_cselect_b32 s99, 0, s99
	v_lshl_add_u64 v[0:1], v[0:1], 0, 64
	v_lshl_add_u64 v[68:69], v[68:69], 0, 64
	v_lshl_add_u64 v[70:71], v[70:71], 0, 64
	s_mov_b32 s100, 0
	s_waitcnt vmcnt(6)
	s_barrier
	v_or_b32_e32 v112, s100, v77
	v_add_u32_e32 v113, v112, v78
	v_add_u32_e32 v112, v112, v79
	ds_read_b128 v[80:83], v113 offset:16384
	ds_read_b128 v[84:87], v113 offset:17408
	ds_read_b128 v[88:91], v113 offset:18432
	ds_read_b128 v[92:95], v113 offset:19456
	ds_read_b128 v[96:99], v112
	ds_read_b128 v[100:103], v112 offset:1024
	ds_read_b128 v[104:107], v112 offset:2048
	ds_read_b128 v[108:111], v112 offset:3072
	s_add_i32 s100, s100, 0x6000
	s_cmp_eq_u32 s100, 0x12000
	s_cselect_b32 s100, 0, s100
	s_bitcmp1_b32 s16, 8
	s_cbranch_scc1 .Lpp_B_1

; template <int MODE, bool SWAP, int MT>
; DI void gemm_tile(const int wv_, const Params& p, const u16* __restrict__ A, const u16* __restrict__ Bt, int brow, int bcol, char* smem, const float* gnext) {
;     ...
;   const int tid = tid_, wid = tid >> 6, lane = tid & 63, wr = wid >> 1, wc = wid & 1, fr = lane & 15, fq = lane >> 4;
;   f32x4 acc[MT][4];
; #pragma unroll
;   for (int m = 0; m < MT; ++m)
; #pragma unroll
;     for (int n = 0; n < 4; ++n) acc[m][n] = f32x4{0.f, 0.f, 0.f, 0.f};
;   const int ra = tid >> 2, cb = (tid & 3) * 8;
;   const u16* ga0 = A + (size_t)(brow + ra) * 1024 + cb;
;   const u16* ga1 = A + (size_t)(brow + 128 + ra) * 1024 + cb;
;   const u16* gb0 = Bt + (size_t)(bcol + ra) * 1024 + cb;
;   auto stage = [&](int t, int buf) {
;     char* sA = smem + buf * 24576; char* sB = sA + 16384;
;     if (MT >= 2 || tid < 256) __builtin_amdgcn_global_load_lds((const unsigned*)(ga0 + t * 32), (unsigned*)(sA + tid * 16), 16, 0, 0);
;     if (MT == 4) __builtin_amdgcn_global_load_lds((const unsigned*)(ga1 + t * 32), (unsigned*)(sA + 8192 + tid * 16), 16, 0, 0);
;     __builtin_amdgcn_global_load_lds((const unsigned*)(gb0 + t * 32), (unsigned*)(sB + tid * 16), 16, 0, 0);
;   };
;   stage(0, 0);
;   for (int t = 0; t < 32; ++t) {
;     asm volatile("s_waitcnt vmcnt(0)" ::: "memory");
;     __syncthreads();
;     if (t + 1 < 32) stage(t + 1, (t + 1) & 1);
;     const char* sA = smem + (t & 1) * 24576; const char* sB = sA + 16384;
;     bf16x8 Af[MT], Bf[4];
; #pragma unroll
;     for (int n = 0; n < 4; ++n) Bf[n] = *(const bf16x8*)(sB + (wc * 64 + n * 16 + fr) * 64 + fq * 16);
;     constexpr int MH = MT >= 2 ? MT / 2 : 1;
; #pragma unroll
;     for (int m = 0; m < MH; ++m) Af[m] = *(const bf16x8*)(sA + (wr * (16 * MT) + m * 16 + fr) * 64 + fq * 16);
.LBB0_88:
	s_and_b64 vcc, exec, s[0:1]
	s_cbranch_vccz .LBB0_83
	s_mov_b32 s1, 0
	v_readlane_b32 s20, v127, 0
	v_mbcnt_lo_u32_b32 v0, -1, s1
	v_mbcnt_hi_u32_b32 v0, -1, v0
	v_add_u32_e32 v12, s33, v0
	s_mov_b32 s1, s16
	v_ashrrev_i32_e32 v13, 2, v12
	v_add_u32_e32 v0, s18, v13
	s_mov_b32 s1, s17
	v_ashrrev_i32_e32 v1, 31, v0
	v_lshlrev_b64 v[4:5], 11, v[0:1]
	v_readlane_b32 s21, v127, 1
	v_lshlrev_b32_e32 v76, 4, v12
	v_lshrrev_b32_e32 v2, 8, v76
	v_sub_u32_e32 v2, 0, v2
	v_lshlrev_b32_e32 v2, 4, v2
	v_xor_b32_e32 v2, v2, v76
	v_and_b32_e32 v2, 48, v2
	v_lshl_add_u64 v[6:7], s[20:21], 0, v[4:5]
	v_add_u32_e32 v0, 0x80, v0
	v_readfirstlane_b32 s1, v76
	v_lshl_add_u64 v[6:7], v[6:7], 0, v[2:3]
	v_ashrrev_i32_e32 v1, 31, v0
	s_mov_b32 m0, s1
	v_lshlrev_b64 v[8:9], 11, v[0:1]
	global_load_lds_dwordx4 v[6:7], off
	v_add_u32_e32 v6, 0x2000, v76
	v_lshl_add_u64 v[0:1], s[20:21], 0, v[8:9]
	v_add_u32_e32 v10, s15, v13
	v_readfirstlane_b32 s1, v6
	v_lshl_add_u64 v[0:1], v[0:1], 0, v[2:3]
	v_ashrrev_i32_e32 v11, 31, v10
	s_mov_b32 m0, s1
	v_lshlrev_b64 v[10:11], 11, v[10:11]
	global_load_lds_dwordx4 v[0:1], off
	v_add_u32_e32 v0, 0x4000, v76
	v_lshl_add_u64 v[10:11], s[2:3], 0, v[10:11]
	v_readfirstlane_b32 s1, v0
	v_lshl_add_u64 v[10:11], v[10:11], 0, v[2:3]
	s_mov_b32 m0, s1
	v_and_b32_e32 v73, 15, v12
	global_load_lds_dwordx4 v[10:11], off
	v_readlane_b32 s20, v127, 22
	v_bfe_u32 v72, v12, 6, 1
	v_ashrrev_i32_e32 v74, 7, v12
	v_lshlrev_b32_e32 v0, 6, v73
	v_or_b32_e32 v4, v4, v2
	v_readlane_b32 s21, v127, 23
	v_lshl_or_b32 v78, v72, 12, v0
	v_lshl_or_b32 v79, v74, 12, v0
	v_lshl_add_u64 v[0:1], s[20:21], 0, v[4:5]
	v_add_u32_e32 v4, s12, v13
	v_subrev_u32_e32 v4, s19, v4
	v_ashrrev_i32_e32 v5, 31, v4
	v_lshlrev_b64 v[4:5], 11, v[4:5]
	v_or_b32_e32 v4, v4, v2
	v_bfe_u32 v75, v12, 4, 2
	v_or_b32_e32 v8, v8, v2
	v_lshl_add_u64 v[70:71], s[4:5], 0, v[4:5]
	v_mov_b32_e32 v4, 0
	s_mov_b32 s0, 0
	v_lshrrev_b32_e32 v77, 2, v73
	v_sub_u32_e32 v77, 0, v77
	v_xor_b32_e32 v77, v77, v75
	v_and_b32_e32 v77, 3, v77
	v_lshlrev_b32_e32 v77, 4, v77
	v_lshl_add_u64 v[68:69], s[20:21], 0, v[8:9]
	v_mov_b32_e32 v5, v4
	v_mov_b32_e32 v6, v4
	v_mov_b32_e32 v7, v4
	v_mov_b32_e32 v8, v4
	v_mov_b32_e32 v9, v4
	v_mov_b32_e32 v10, v4
	v_mov_b32_e32 v11, v4
	v_mov_b32_e32 v12, v4
	v_mov_b32_e32 v13, v4
	v_mov_b32_e32 v14, v4
	v_mov_b32_e32 v15, v4
	v_mov_b32_e32 v16, v4
	v_mov_b32_e32 v17, v4
	v_mov_b32_e32 v18, v4
	v_mov_b32_e32 v19, v4
	v_mov_b32_e32 v20, v4
	v_mov_b32_e32 v21, v4
	v_mov_b32_e32 v22, v4
	v_mov_b32_e32 v23, v4
	v_mov_b32_e32 v24, v4
	v_mov_b32_e32 v25, v4
	v_mov_b32_e32 v26, v4
	v_mov_b32_e32 v27, v4
	v_mov_b32_e32 v28, v4
	v_mov_b32_e32 v29, v4
	v_mov_b32_e32 v30, v4
	v_mov_b32_e32 v31, v4
	v_mov_b32_e32 v32, v4
	v_mov_b32_e32 v33, v4
	v_mov_b32_e32 v34, v4
	v_mov_b32_e32 v35, v4
	v_mov_b32_e32 v36, v4
	v_mov_b32_e32 v37, v4
	v_mov_b32_e32 v38, v4
	v_mov_b32_e32 v39, v4
	v_mov_b32_e32 v40, v4
	v_mov_b32_e32 v41, v4
	v_mov_b32_e32 v42, v4
	v_mov_b32_e32 v43, v4
	v_mov_b32_e32 v44, v4
	v_mov_b32_e32 v45, v4
	v_mov_b32_e32 v46, v4
	v_mov_b32_e32 v47, v4
	v_mov_b32_e32 v48, v4
	v_mov_b32_e32 v49, v4
	v_mov_b32_e32 v50, v4
	v_mov_b32_e32 v51, v4
	v_mov_b32_e32 v52, v4
	v_mov_b32_e32 v53, v4
	v_mov_b32_e32 v54, v4
	v_mov_b32_e32 v55, v4
	v_mov_b32_e32 v56, v4
	v_mov_b32_e32 v57, v4
	v_mov_b32_e32 v58, v4
	v_mov_b32_e32 v59, v4
	v_mov_b32_e32 v60, v4
	v_mov_b32_e32 v61, v4
	v_mov_b32_e32 v62, v4
	v_mov_b32_e32 v63, v4
	v_mov_b32_e32 v64, v4
	v_mov_b32_e32 v65, v4
	v_mov_b32_e32 v66, v4
	v_mov_b32_e32 v67, v4
	v_readlane_b32 s22, v127, 2
	v_readlane_b32 s23, v127, 3
	v_readfirstlane_b32 s98, v76
	s_movk_i32 s99, 0x6000
	s_add_i32 s101, s98, s99
	s_mov_b32 m0, s101
	s_add_i32 s101, s101, 0x2000
	global_load_lds_dwordx4 v[0:1], off
	s_mov_b32 m0, s101
	s_add_i32 s101, s101, 0x2000
	global_load_lds_dwordx4 v[68:69], off
	s_mov_b32 m0, s101
	s_add_i32 s99, s99, 0x6000
	global_load_lds_dwordx4 v[70:71], off
	s_cmp_eq_u32 s99, 0x12000
	s_cselect_b32 s99, 0, s99
	v_lshl_add_u64 v[0:1], v[0:1], 0, 64
	v_lshl_add_u64 v[68:69], v[68:69], 0, 64
	v_lshl_add_u64 v[70:71], v[70:71], 0, 64
	s_add_i32 s101, s98, s99
	s_mov_b32 m0, s101
	s_add_i32 s101, s101, 0x2000
	global_load_lds_dwordx4 v[0:1], off
	s_mov_b32 m0, s101
	s_add_i32 s101, s101, 0x2000
	global_load_lds_dwordx4 v[68:69], off
	s_mov_b32 m0, s101
	s_add_i32 s99, s99, 0x6000
	global_load_lds_dwordx4 v[70:71], off
	s_cmp_eq_u32 s99, 0x12000
	s_cselect_b32 s99, 0, s99
	v_lshl_add_u64 v[0:1], v[0:1], 0, 64
	v_lshl_add_u64 v[68:69], v[68:69], 0, 64
	v_lshl_add_u64 v[70:71], v[70:71], 0, 64
	s_mov_b32 s100, 0
	s_waitcnt vmcnt(6)
	s_barrier
	v_or_b32_e32 v112, s100, v77
	v_add_u32_e32 v113, v112, v78
	v_add_u32_e32 v112, v112, v79
	ds_read_b128 v[80:83], v113 offset:16384
	ds_read_b128 v[84:87], v113 offset:17408
	ds_read_b128 v[88:91], v113 offset:18432
	ds_read_b128 v[92:95], v113 offset:19456
	ds_read_b128 v[96:99], v112
	ds_read_b128 v[100:103], v112 offset:1024
	ds_read_b128 v[104:107], v112 offset:2048
	ds_read_b128 v[108:111], v112 offset:3072
	s_add_i32 s100, s100, 0x6000
	s_cmp_eq_u32 s100, 0x12000
	s_cselect_b32 s100, 0, s100
	s_bitcmp1_b32 s16, 8
	s_cbranch_scc1 .Lpp_B_2

; template <int MODE, bool SWAP, int MT>
; DI void gemm_tile(const int wv_, const Params& p, const u16* __restrict__ A, const u16* __restrict__ Bt, int brow, int bcol, char* smem, const float* gnext) {
;     ...
;   const int tid = tid_, wid = tid >> 6, lane = tid & 63, wr = wid >> 1, wc = wid & 1, fr = lane & 15, fq = lane >> 4;
;   f32x4 acc[MT][4];
; #pragma unroll
;   for (int m = 0; m < MT; ++m)
; #pragma unroll
;     for (int n = 0; n < 4; ++n) acc[m][n] = f32x4{0.f, 0.f, 0.f, 0.f};
;   const int ra = tid >> 2, cb = (tid & 3) * 8;
;   const u16* ga0 = A + (size_t)(brow + ra) * 1024 + cb;
;   const u16* ga1 = A + (size_t)(brow + 128 + ra) * 1024 + cb;
;   const u16* gb0 = Bt + (size_t)(bcol + ra) * 1024 + cb;
;   auto stage = [&](int t, int buf) {
;     char* sA = smem + buf * 24576; char* sB = sA + 16384;
;     if (MT >= 2 || tid < 256) __builtin_amdgcn_global_load_lds((const unsigned*)(ga0 + t * 32), (unsigned*)(sA + tid * 16), 16, 0, 0);
;     if (MT == 4) __builtin_amdgcn_global_load_lds((const unsigned*)(ga1 + t * 32), (unsigned*)(sA + 8192 + tid * 16), 16, 0, 0);
;     __builtin_amdgcn_global_load_lds((const unsigned*)(gb0 + t * 32), (unsigned*)(sB + tid * 16), 16, 0, 0);
;   };
;   stage(0, 0);
;   for (int t = 0; t < 32; ++t) {
;     asm volatile("s_waitcnt vmcnt(0)" ::: "memory");
;     __syncthreads();
;     if (t + 1 < 32) stage(t + 1, (t + 1) & 1);
;     const char* sA = smem + (t & 1) * 24576; const char* sB = sA + 16384;
;     bf16x8 Af[MT], Bf[4];
; #pragma unroll
;     for (int n = 0; n < 4; ++n) Bf[n] = *(const bf16x8*)(sB + (wc * 64 + n * 16 + fr) * 64 + fq * 16);
;     constexpr int MH = MT >= 2 ? MT / 2 : 1;
; #pragma unroll
;     for (int m = 0; m < MH; ++m) Af[m] = *(const bf16x8*)(sA + (wr * (16 * MT) + m * 16 + fr) * 64 + fq * 16);
.LBB0_372:
	s_mul_hi_i32 s0, s22, 0x3e0f83e1
	s_mov_b32 s7, 0
	s_lshr_b32 s1, s0, 31
	s_ashr_i32 s0, s0, 3
	s_add_i32 s6, s0, s1
	v_mbcnt_lo_u32_b32 v0, -1, s7
	v_mbcnt_hi_u32_b32 v0, -1, v0
	s_mul_i32 s0, s6, 0xffffffdf
	v_add_u32_e32 v2, s33, v0
	s_add_i32 s1, s0, s22
	s_lshl_b32 s0, s6, 8
	s_mov_b32 s7, s16
	v_ashrrev_i32_e32 v12, 2, v2
	v_add_u32_e32 v0, s0, v12
	s_mov_b32 s7, s17
	v_ashrrev_i32_e32 v1, 31, v0
	v_readlane_b32 s8, v127, 0
	v_lshlrev_b64 v[4:5], 11, v[0:1]
	v_readlane_b32 s9, v127, 1
	v_lshlrev_b32_e32 v76, 4, v2
	v_bfe_u32 v72, v2, 6, 1
	v_ashrrev_i32_e32 v74, 7, v2
	v_and_b32_e32 v75, 15, v2
	v_bfe_u32 v73, v2, 4, 2
	v_lshl_add_u64 v[6:7], s[8:9], 0, v[4:5]
	v_lshrrev_b32_e32 v2, 8, v76
	v_sub_u32_e32 v2, 0, v2
	v_lshlrev_b32_e32 v2, 4, v2
	v_xor_b32_e32 v2, v2, v76
	v_and_b32_e32 v2, 48, v2
	v_add_u32_e32 v0, 0x80, v0
	v_readfirstlane_b32 s7, v76
	v_lshl_add_u64 v[6:7], v[6:7], 0, v[2:3]
	v_ashrrev_i32_e32 v1, 31, v0
	s_mov_b32 m0, s7
	s_lshl_b32 s23, s1, 7
	v_lshlrev_b64 v[8:9], 11, v[0:1]
	global_load_lds_dwordx4 v[6:7], off
	v_add_u32_e32 v6, 0x2000, v76
	v_lshl_add_u64 v[0:1], s[8:9], 0, v[8:9]
	v_add_u32_e32 v10, s23, v12
	v_readfirstlane_b32 s7, v6
	v_lshl_add_u64 v[0:1], v[0:1], 0, v[2:3]
	v_ashrrev_i32_e32 v11, 31, v10
	s_mov_b32 m0, s7
	v_lshlrev_b64 v[10:11], 11, v[10:11]
	global_load_lds_dwordx4 v[0:1], off
	v_add_u32_e32 v0, 0x4000, v76
	v_lshl_add_u64 v[10:11], s[2:3], 0, v[10:11]
	v_readfirstlane_b32 s7, v0
	v_lshl_add_u64 v[10:11], v[10:11], 0, v[2:3]
	s_mov_b32 m0, s7
	v_readlane_b32 s8, v127, 22
	global_load_lds_dwordx4 v[10:11], off
	v_lshlrev_b32_e32 v0, 6, v75
	v_or_b32_e32 v4, v4, v2
	v_readlane_b32 s9, v127, 23
	v_lshl_or_b32 v78, v72, 12, v0
	v_lshl_or_b32 v79, v74, 12, v0
	v_lshl_add_u64 v[0:1], s[8:9], 0, v[4:5]
	v_add_u32_e32 v4, s20, v12
	s_mulk_i32 s6, 0x1080
	v_subrev_u32_e32 v4, s6, v4
	v_ashrrev_i32_e32 v5, 31, v4
	v_lshlrev_b64 v[4:5], 11, v[4:5]
	v_or_b32_e32 v4, v4, v2
	v_or_b32_e32 v8, v8, v2
	v_lshl_add_u64 v[70:71], s[4:5], 0, v[4:5]
	v_mov_b32_e32 v4, 0
	s_mov_b32 s1, 0
	v_lshrrev_b32_e32 v77, 2, v75
	v_sub_u32_e32 v77, 0, v77
	v_xor_b32_e32 v77, v77, v73
	v_and_b32_e32 v77, 3, v77
	v_lshlrev_b32_e32 v77, 4, v77
	v_lshl_add_u64 v[68:69], s[8:9], 0, v[8:9]
	v_mov_b32_e32 v5, v4
	v_mov_b32_e32 v6, v4
	v_mov_b32_e32 v7, v4
	v_mov_b32_e32 v8, v4
	v_mov_b32_e32 v9, v4
	v_mov_b32_e32 v10, v4
	v_mov_b32_e32 v11, v4
	v_mov_b32_e32 v12, v4
	v_mov_b32_e32 v13, v4
	v_mov_b32_e32 v14, v4
	v_mov_b32_e32 v15, v4
	v_mov_b32_e32 v16, v4
	v_mov_b32_e32 v17, v4
	v_mov_b32_e32 v18, v4
	v_mov_b32_e32 v19, v4
	v_mov_b32_e32 v20, v4
	v_mov_b32_e32 v21, v4
	v_mov_b32_e32 v22, v4
	v_mov_b32_e32 v23, v4
	v_mov_b32_e32 v24, v4
	v_mov_b32_e32 v25, v4
	v_mov_b32_e32 v26, v4
	v_mov_b32_e32 v27, v4
	v_mov_b32_e32 v28, v4
	v_mov_b32_e32 v29, v4
	v_mov_b32_e32 v30, v4
	v_mov_b32_e32 v31, v4
	v_mov_b32_e32 v32, v4
	v_mov_b32_e32 v33, v4
	v_mov_b32_e32 v34, v4
	v_mov_b32_e32 v35, v4
	v_mov_b32_e32 v44, v4
	v_mov_b32_e32 v45, v4
	v_mov_b32_e32 v46, v4
	v_mov_b32_e32 v47, v4
	v_mov_b32_e32 v36, v4
	v_mov_b32_e32 v37, v4
	v_mov_b32_e32 v38, v4
	v_mov_b32_e32 v39, v4
	v_mov_b32_e32 v40, v4
	v_mov_b32_e32 v41, v4
	v_mov_b32_e32 v42, v4
	v_mov_b32_e32 v43, v4
	v_mov_b32_e32 v48, v4
	v_mov_b32_e32 v49, v4
	v_mov_b32_e32 v50, v4
	v_mov_b32_e32 v51, v4
	v_mov_b32_e32 v52, v4
	v_mov_b32_e32 v53, v4
	v_mov_b32_e32 v54, v4
	v_mov_b32_e32 v55, v4
	v_mov_b32_e32 v56, v4
	v_mov_b32_e32 v57, v4
	v_mov_b32_e32 v58, v4
	v_mov_b32_e32 v59, v4
	v_mov_b32_e32 v60, v4
	v_mov_b32_e32 v61, v4
	v_mov_b32_e32 v62, v4
	v_mov_b32_e32 v63, v4
	v_mov_b32_e32 v64, v4
	v_mov_b32_e32 v65, v4
	v_mov_b32_e32 v66, v4
	v_mov_b32_e32 v67, v4
	v_readlane_b32 s10, v127, 2
	v_readlane_b32 s11, v127, 3
	v_readfirstlane_b32 s98, v76
	s_movk_i32 s99, 0x6000
	s_add_i32 s101, s98, s99
	s_mov_b32 m0, s101
	s_add_i32 s101, s101, 0x2000
	global_load_lds_dwordx4 v[0:1], off
	s_mov_b32 m0, s101
	s_add_i32 s101, s101, 0x2000
	global_load_lds_dwordx4 v[68:69], off
	s_mov_b32 m0, s101
	s_add_i32 s99, s99, 0x6000
	global_load_lds_dwordx4 v[70:71], off
	s_cmp_eq_u32 s99, 0x12000
	s_cselect_b32 s99, 0, s99
	v_lshl_add_u64 v[0:1], v[0:1], 0, 64
	v_lshl_add_u64 v[68:69], v[68:69], 0, 64
	v_lshl_add_u64 v[70:71], v[70:71], 0, 64
	s_add_i32 s101, s98, s99
	s_mov_b32 m0, s101
	s_add_i32 s101, s101, 0x2000
	global_load_lds_dwordx4 v[0:1], off
	s_mov_b32 m0, s101
	s_add_i32 s101, s101, 0x2000
	global_load_lds_dwordx4 v[68:69], off
	s_mov_b32 m0, s101
	s_add_i32 s99, s99, 0x6000
	global_load_lds_dwordx4 v[70:71], off
	s_cmp_eq_u32 s99, 0x12000
	s_cselect_b32 s99, 0, s99
	v_lshl_add_u64 v[0:1], v[0:1], 0, 64
	v_lshl_add_u64 v[68:69], v[68:69], 0, 64
	v_lshl_add_u64 v[70:71], v[70:71], 0, 64
	s_mov_b32 s100, 0
	s_waitcnt vmcnt(6)
	s_barrier
	v_or_b32_e32 v112, s100, v77
	v_add_u32_e32 v113, v112, v78
	v_add_u32_e32 v112, v112, v79
	ds_read_b128 v[80:83], v113 offset:16384
	ds_read_b128 v[84:87], v113 offset:17408
	ds_read_b128 v[88:91], v113 offset:18432
	ds_read_b128 v[92:95], v113 offset:19456
	ds_read_b128 v[96:99], v112
	ds_read_b128 v[100:103], v112 offset:1024
	ds_read_b128 v[104:107], v112 offset:2048
	ds_read_b128 v[108:111], v112 offset:3072
	s_add_i32 s100, s100, 0x6000
	s_cmp_eq_u32 s100, 0x12000
	s_cselect_b32 s100, 0, s100
	s_bitcmp1_b32 s16, 8
	s_cbranch_scc1 .Lpp_B_3

; template <int MODE, bool SWAP, int MT>
; DI void gemm_tile(const int wv_, const Params& p, const u16* __restrict__ A, const u16* __restrict__ Bt, int brow, int bcol, char* smem, const float* gnext) {
;     ...
;   const int tid = tid_, wid = tid >> 6, lane = tid & 63, wr = wid >> 1, wc = wid & 1, fr = lane & 15, fq = lane >> 4;
;   f32x4 acc[MT][4];
; #pragma unroll
;   for (int m = 0; m < MT; ++m)
; #pragma unroll
;     for (int n = 0; n < 4; ++n) acc[m][n] = f32x4{0.f, 0.f, 0.f, 0.f};
;   const int ra = tid >> 2, cb = (tid & 3) * 8;
;   const u16* ga0 = A + (size_t)(brow + ra) * 1024 + cb;
;   const u16* ga1 = A + (size_t)(brow + 128 + ra) * 1024 + cb;
;   const u16* gb0 = Bt + (size_t)(bcol + ra) * 1024 + cb;
;   auto stage = [&](int t, int buf) {
;     char* sA = smem + buf * 24576; char* sB = sA + 16384;
;     if (MT >= 2 || tid < 256) __builtin_amdgcn_global_load_lds((const unsigned*)(ga0 + t * 32), (unsigned*)(sA + tid * 16), 16, 0, 0);
;     if (MT == 4) __builtin_amdgcn_global_load_lds((const unsigned*)(ga1 + t * 32), (unsigned*)(sA + 8192 + tid * 16), 16, 0, 0);
;     __builtin_amdgcn_global_load_lds((const unsigned*)(gb0 + t * 32), (unsigned*)(sB + tid * 16), 16, 0, 0);
;   };
;   stage(0, 0);
;   for (int t = 0; t < 32; ++t) {
;     asm volatile("s_waitcnt vmcnt(0)" ::: "memory");
;     __syncthreads();
;     if (t + 1 < 32) stage(t + 1, (t + 1) & 1);
;     const char* sA = smem + (t & 1) * 24576; const char* sB = sA + 16384;
;     bf16x8 Af[MT], Bf[4];
; #pragma unroll
;     for (int n = 0; n < 4; ++n) Bf[n] = *(const bf16x8*)(sB + (wc * 64 + n * 16 + fr) * 64 + fq * 16);
;     constexpr int MH = MT >= 2 ? MT / 2 : 1;
; #pragma unroll
;     for (int m = 0; m < MH; ++m) Af[m] = *(const bf16x8*)(sA + (wr * (16 * MT) + m * 16 + fr) * 64 + fq * 16);
.LBB0_828:
	s_ashr_i32 s0, s28, 31
	s_mov_b32 s3, 0
	s_lshr_b32 s0, s0, 29
	s_add_i32 s0, s28, s0
	v_mbcnt_lo_u32_b32 v0, -1, s3
	v_mbcnt_hi_u32_b32 v0, -1, v0
	s_ashr_i32 s1, s0, 3
	v_add_u32_e32 v77, s33, v0
	s_lshl_b32 s0, s1, 8
	s_mov_b32 s3, s16
	v_ashrrev_i32_e32 v12, 2, v77
	v_add_u32_e32 v0, s0, v12
	s_mov_b32 s3, s17
	s_waitcnt lgkmcnt(0)
	v_ashrrev_i32_e32 v1, 31, v0
	v_lshlrev_b64 v[4:5], 11, v[0:1]
	v_lshlrev_b32_e32 v74, 4, v77
	v_lshl_add_u64 v[6:7], s[50:51], 0, v[4:5]
	v_lshrrev_b32_e32 v2, 8, v74
	v_sub_u32_e32 v2, 0, v2
	v_lshlrev_b32_e32 v2, 4, v2
	v_xor_b32_e32 v2, v2, v74
	v_and_b32_e32 v2, 48, v2
	v_add_u32_e32 v0, 0x80, v0
	v_readfirstlane_b32 s3, v74
	s_lshl_b32 s2, s1, 10
	s_lshl_b32 s1, s28, 7
	v_lshl_add_u64 v[6:7], v[6:7], 0, v[2:3]
	v_ashrrev_i32_e32 v1, 31, v0
	s_mov_b32 m0, s3
	s_sub_i32 s12, s1, s2
	v_lshlrev_b64 v[8:9], 11, v[0:1]
	global_load_lds_dwordx4 v[6:7], off
	v_add_u32_e32 v6, 0x2000, v74
	v_lshl_add_u64 v[0:1], s[50:51], 0, v[8:9]
	v_add_u32_e32 v10, s12, v12
	v_readfirstlane_b32 s3, v6
	v_lshl_add_u64 v[0:1], v[0:1], 0, v[2:3]
	v_ashrrev_i32_e32 v11, 31, v10
	s_mov_b32 m0, s3
	v_lshlrev_b64 v[10:11], 11, v[10:11]
	global_load_lds_dwordx4 v[0:1], off
	v_add_u32_e32 v0, 0x4000, v74
	v_lshl_add_u64 v[10:11], s[6:7], 0, v[10:11]
	v_readfirstlane_b32 s3, v0
	v_lshl_add_u64 v[10:11], v[10:11], 0, v[2:3]
	s_mov_b32 m0, s3
	v_and_b32_e32 v73, 15, v77
	global_load_lds_dwordx4 v[10:11], off
	v_readlane_b32 s4, v127, 28
	v_bfe_u32 v76, v77, 6, 1
	v_ashrrev_i32_e32 v72, 7, v77
	v_lshlrev_b32_e32 v0, 6, v73
	v_or_b32_e32 v4, v4, v2
	v_readlane_b32 s5, v127, 29
	v_lshl_or_b32 v78, v76, 12, v0
	v_lshl_or_b32 v79, v72, 12, v0
	v_lshl_add_u64 v[0:1], s[4:5], 0, v[4:5]
	v_add_u32_e32 v4, s23, v12
	v_subrev_u32_e32 v4, s2, v4
	v_ashrrev_i32_e32 v5, 31, v4
	v_lshlrev_b64 v[4:5], 11, v[4:5]
	v_readlane_b32 s2, v127, 30
	v_or_b32_e32 v4, v4, v2
	v_readlane_b32 s3, v127, 31
	v_or_b32_e32 v8, v8, v2
	s_mov_b32 s1, 0
	v_lshl_add_u64 v[70:71], s[2:3], 0, v[4:5]
	v_mov_b32_e32 v4, 0
	v_lshrrev_b32_e32 v75, 2, v73
	v_sub_u32_e32 v75, 0, v75
	v_lshlrev_b32_e32 v75, 4, v75
	v_xor_b32_e32 v75, v75, v77
	v_and_b32_e32 v75, 48, v75
	v_lshl_add_u64 v[68:69], s[4:5], 0, v[8:9]
	v_mov_b32_e32 v5, v4
	v_mov_b32_e32 v6, v4
	v_mov_b32_e32 v7, v4
	v_mov_b32_e32 v8, v4
	v_mov_b32_e32 v9, v4
	v_mov_b32_e32 v10, v4
	v_mov_b32_e32 v11, v4
	v_mov_b32_e32 v12, v4
	v_mov_b32_e32 v13, v4
	v_mov_b32_e32 v14, v4
	v_mov_b32_e32 v15, v4
	v_mov_b32_e32 v16, v4
	v_mov_b32_e32 v17, v4
	v_mov_b32_e32 v18, v4
	v_mov_b32_e32 v19, v4
	v_mov_b32_e32 v20, v4
	v_mov_b32_e32 v21, v4
	v_mov_b32_e32 v22, v4
	v_mov_b32_e32 v23, v4
	v_mov_b32_e32 v24, v4
	v_mov_b32_e32 v25, v4
	v_mov_b32_e32 v26, v4
	v_mov_b32_e32 v27, v4
	v_mov_b32_e32 v28, v4
	v_mov_b32_e32 v29, v4
	v_mov_b32_e32 v30, v4
	v_mov_b32_e32 v31, v4
	v_mov_b32_e32 v32, v4
	v_mov_b32_e32 v33, v4
	v_mov_b32_e32 v34, v4
	v_mov_b32_e32 v35, v4
	v_mov_b32_e32 v36, v4
	v_mov_b32_e32 v37, v4
	v_mov_b32_e32 v38, v4
	v_mov_b32_e32 v39, v4
	v_mov_b32_e32 v40, v4
	v_mov_b32_e32 v41, v4
	v_mov_b32_e32 v42, v4
	v_mov_b32_e32 v43, v4
	v_mov_b32_e32 v44, v4
	v_mov_b32_e32 v45, v4
	v_mov_b32_e32 v46, v4
	v_mov_b32_e32 v47, v4
	v_mov_b32_e32 v48, v4
	v_mov_b32_e32 v49, v4
	v_mov_b32_e32 v50, v4
	v_mov_b32_e32 v51, v4
	v_mov_b32_e32 v52, v4
	v_mov_b32_e32 v53, v4
	v_mov_b32_e32 v54, v4
	v_mov_b32_e32 v55, v4
	v_mov_b32_e32 v56, v4
	v_mov_b32_e32 v57, v4
	v_mov_b32_e32 v58, v4
	v_mov_b32_e32 v59, v4
	v_mov_b32_e32 v60, v4
	v_mov_b32_e32 v61, v4
	v_mov_b32_e32 v62, v4
	v_mov_b32_e32 v63, v4
	v_mov_b32_e32 v64, v4
	v_mov_b32_e32 v65, v4
	v_mov_b32_e32 v66, v4
	v_mov_b32_e32 v67, v4
	v_readfirstlane_b32 s98, v74
	s_movk_i32 s99, 0x6000
	s_add_i32 s101, s98, s99
	s_mov_b32 m0, s101
	s_add_i32 s101, s101, 0x2000
	global_load_lds_dwordx4 v[0:1], off
	s_mov_b32 m0, s101
	s_add_i32 s101, s101, 0x2000
	global_load_lds_dwordx4 v[68:69], off
	s_mov_b32 m0, s101
	s_add_i32 s99, s99, 0x6000
	global_load_lds_dwordx4 v[70:71], off
	s_cmp_eq_u32 s99, 0x12000
	s_cselect_b32 s99, 0, s99
	v_lshl_add_u64 v[0:1], v[0:1], 0, 64
	v_lshl_add_u64 v[68:69], v[68:69], 0, 64
	v_lshl_add_u64 v[70:71], v[70:71], 0, 64
	s_add_i32 s101, s98, s99
	s_mov_b32 m0, s101
	s_add_i32 s101, s101, 0x2000
	global_load_lds_dwordx4 v[0:1], off
	s_mov_b32 m0, s101
	s_add_i32 s101, s101, 0x2000
	global_load_lds_dwordx4 v[68:69], off
	s_mov_b32 m0, s101
	s_add_i32 s99, s99, 0x6000
	global_load_lds_dwordx4 v[70:71], off
	s_cmp_eq_u32 s99, 0x12000
	s_cselect_b32 s99, 0, s99
	v_lshl_add_u64 v[0:1], v[0:1], 0, 64
	v_lshl_add_u64 v[68:69], v[68:69], 0, 64
	v_lshl_add_u64 v[70:71], v[70:71], 0, 64
	s_mov_b32 s100, 0
	s_waitcnt vmcnt(6)
	s_barrier
	v_or_b32_e32 v112, s100, v75
	v_add_u32_e32 v113, v112, v78
	v_add_u32_e32 v112, v112, v79
	ds_read_b128 v[80:83], v113 offset:16384
	ds_read_b128 v[84:87], v113 offset:17408
	ds_read_b128 v[88:91], v113 offset:18432
	ds_read_b128 v[92:95], v113 offset:19456
	ds_read_b128 v[96:99], v112
	ds_read_b128 v[100:103], v112 offset:1024
	ds_read_b128 v[104:107], v112 offset:2048
	ds_read_b128 v[108:111], v112 offset:3072
	s_add_i32 s100, s100, 0x6000
	s_cmp_eq_u32 s100, 0x12000
	s_cselect_b32 s100, 0, s100
	s_bitcmp1_b32 s16, 8
	s_cbranch_scc1 .Lpp_B_4
